# latent attention loop: waves 4-7 take the per-tile barrier right after P.V (before their register-only softmax tail), waves 0-3 at the end: fixed stagger of SIMD partners
# speedup vs baseline: 1.0160x; 1.0043x over previous
.LBB0_855:
	s_add_i32 s11, s11, 2
	s_add_i32 m0, s100, 0x4000
	s_nop 0
	global_load_lds_dwordx4 v178, s[14:15]
	s_add_i32 m0, s100, 0x4400
	s_nop 0
	global_load_lds_dwordx4 v179, s[14:15]
	s_sub_i32 s0, s13, 64
	s_cmp_lt_u32 s11, 3
	s_cselect_b32 s0, s12, s0
	s_ashr_i32 s1, s0, 31
	s_lshl_b64 s[14:15], s[0:1], 10
	s_add_u32 s14, s9, s14
	s_addc_u32 s15, s10, s15
	s_mul_hi_i32 s1, s0, 0x600
	s_mulk_i32 s0, 0x600
	s_add_u32 s0, s2, s0
	s_addc_u32 s1, s8, s1
	s_add_i32 m0, s101, 0x8000
	s_nop 0
	global_load_lds_dwordx4 v180, s[0:1]
	s_add_i32 m0, s101, 0x8400
	s_nop 0
	global_load_lds_dwordx4 v181, s[0:1]
	s_add_i32 m0, s101, 0x8800
	s_nop 0
	global_load_lds_dwordx4 v182, s[0:1]
	ds_read_b128 v[66:69], v183 offset:57344
	ds_read_b128 v[70:73], v226 offset:57344
	ds_read_b128 v[234:237], v184 offset:57344
	ds_read_b128 v[238:241], v225 offset:57344
	v_add_f32_e32 v152, 0, v153
	v_add_f32_e32 v152, v154, v152
	s_waitcnt lgkmcnt(2)
	v_mfma_f32_32x32x16_bf16 v[82:97], v[66:69], v[128:131], 0
	v_add_f32_e32 v152, v230, v152
	v_add_f32_e32 v152, v231, v152
	v_add_f32_e32 v152, v232, v152
	v_add_f32_e32 v152, v233, v152
	v_add_f32_e32 v152, v155, v152
	v_add_f32_e32 v152, v229, v152
	v_add_f32_e32 v152, v151, v152
	v_mfma_f32_32x32x16_bf16 v[66:81], v[70:73], v[128:131], 0
	ds_read_b128 v[162:165], v185 offset:57344
	ds_read_b128 v[166:169], v224 offset:57344
	v_add_f32_e32 v152, v156, v152
	v_add_f32_e32 v152, v157, v152
	v_add_f32_e32 v152, v158, v152
	v_exp_f32_e32 v144, v144
	v_add_f32_e32 v152, v148, v152
	v_exp_f32_e32 v145, v145
	v_add_f32_e32 v152, v149, v152
	s_waitcnt lgkmcnt(2)
	v_mfma_f32_32x32x16_bf16 v[82:97], v[234:237], v[124:127], v[82:97]
	v_exp_f32_e32 v142, v142
	v_add_f32_e32 v152, v150, v152
	v_exp_f32_e32 v143, v143
	v_add_f32_e32 v152, v159, v152
	v_exp_f32_e32 v136, v136
	v_add_f32_e32 v152, v144, v152
	v_exp_f32_e32 v137, v137
	v_mfma_f32_32x32x16_bf16 v[66:81], v[238:241], v[124:127], v[66:81]
	ds_read_b128 v[234:237], v186 offset:57344
	ds_read_b128 v[238:241], v223 offset:57344
	v_add_f32_e32 v152, v145, v152
	v_exp_f32_e32 v134, v134
	v_add_f32_e32 v152, v142, v152
	v_exp_f32_e32 v135, v135
	v_add_f32_e32 v152, v143, v152
	v_exp_f32_e32 v132, v132
	s_waitcnt lgkmcnt(2)
	v_mfma_f32_32x32x16_bf16 v[82:97], v[162:165], v[120:123], v[82:97]
	v_add_f32_e32 v152, v136, v152
	v_exp_f32_e32 v133, v133
	v_add_f32_e32 v152, v137, v152
	v_exp_f32_e32 v146, v146
	v_add_f32_e32 v152, v134, v152
	v_exp_f32_e32 v147, v147
	v_add_f32_e32 v152, v135, v152
	v_mfma_f32_32x32x16_bf16 v[66:81], v[166:169], v[120:123], v[66:81]
	ds_read_b128 v[162:165], v187 offset:57344
	ds_read_b128 v[166:169], v222 offset:57344
	v_exp_f32_e32 v140, v140
	v_add_f32_e32 v152, v132, v152
	v_exp_f32_e32 v141, v141
	v_add_f32_e32 v152, v133, v152
	v_exp_f32_e32 v138, v138
	v_add_f32_e32 v152, v146, v152
	s_waitcnt lgkmcnt(2)
	v_mfma_f32_32x32x16_bf16 v[82:97], v[234:237], v[116:119], v[82:97]
	v_exp_f32_e32 v139, v139
	v_add_f32_e32 v152, v147, v152
	v_add_f32_e32 v152, v140, v152
	v_add_f32_e32 v152, v141, v152
	v_add_f32_e32 v152, v138, v152
	v_add_f32_e32 v227, v139, v152
	v_mov_b32_e32 v228, v227
	v_mfma_f32_32x32x16_bf16 v[66:81], v[238:241], v[116:119], v[66:81]
	ds_read_b128 v[234:237], v188 offset:57344
	ds_read_b128 v[238:241], v221 offset:57344
	v_cvt_pk_bf16_f32 v152, v153, v154
	v_cvt_pk_bf16_f32 v154, v232, v233
	v_permlane32_swap_b32_e32 v227, v228
	v_cvt_pk_bf16_f32 v153, v230, v231
	v_cvt_pk_bf16_f32 v155, v155, v229
	s_waitcnt lgkmcnt(2)
	v_mfma_f32_32x32x16_bf16 v[82:97], v[162:165], v[112:115], v[82:97]
	v_permlane32_swap_b32_e32 v152, v154
	v_cvt_pk_bf16_f32 v156, v151, v156
	v_cvt_pk_bf16_f32 v157, v157, v158
	v_cvt_pk_bf16_f32 v158, v148, v149
	v_cvt_pk_bf16_f32 v159, v150, v159
	v_cvt_pk_bf16_f32 v230, v144, v145
	v_mfma_f32_32x32x16_bf16 v[66:81], v[166:169], v[112:115], v[66:81]
	ds_read_b128 v[162:165], v189 offset:57344
	ds_read_b128 v[166:169], v220 offset:57344
	v_cvt_pk_bf16_f32 v231, v142, v143
	v_cvt_pk_bf16_f32 v232, v136, v137
	v_cvt_pk_bf16_f32 v233, v134, v135
	v_permlane32_swap_b32_e32 v153, v155
	v_permlane32_swap_b32_e32 v156, v158
	s_waitcnt lgkmcnt(2)
	v_mfma_f32_32x32x16_bf16 v[82:97], v[234:237], v[108:111], v[82:97]
	v_permlane32_swap_b32_e32 v157, v159
	v_permlane32_swap_b32_e32 v230, v232
	v_permlane32_swap_b32_e32 v231, v233
	v_mfma_f32_32x32x16_bf16 v[66:81], v[238:241], v[108:111], v[66:81]
	ds_read_b128 v[234:237], v190 offset:57344
	ds_read_b128 v[238:241], v219 offset:57344
	s_waitcnt lgkmcnt(2)
	v_mfma_f32_32x32x16_bf16 v[82:97], v[162:165], v[104:107], v[82:97]
	v_mfma_f32_32x32x16_bf16 v[66:81], v[166:169], v[104:107], v[66:81]
	ds_read_b128 v[162:165], v191 offset:57344
	ds_read_b128 v[166:169], v218 offset:57344
	ds_read_b128 v[242:245], v192
	s_waitcnt lgkmcnt(3)
	v_mfma_f32_32x32x16_bf16 v[82:97], v[234:237], v[100:103], v[82:97]
	v_mfma_f32_32x32x16_bf16 v[66:81], v[238:241], v[100:103], v[66:81]
	ds_read_b128 v[234:237], v194 offset:57344
	ds_read_b128 v[238:241], v217 offset:57344
	ds_read_b128 v[246:249], v176
	s_waitcnt lgkmcnt(3)
	v_mfma_f32_32x32x16_bf16 v[82:97], v[162:165], v[242:245], v[82:97]
	v_mfma_f32_32x32x16_bf16 v[66:81], v[166:169], v[242:245], v[66:81]
	ds_read_b128 v[162:165], v195 offset:57344
	ds_read_b128 v[166:169], v216 offset:57344
	ds_read_b128 v[242:245], v177
	s_waitcnt lgkmcnt(3)
	v_mfma_f32_32x32x16_bf16 v[82:97], v[234:237], v[246:249], v[82:97]
	v_mfma_f32_32x32x16_bf16 v[66:81], v[238:241], v[246:249], v[66:81]
	ds_read_b128 v[234:237], v196 offset:57344
	ds_read_b128 v[238:241], v215 offset:57344
	ds_read_b128 v[246:249], v175
	s_waitcnt lgkmcnt(3)
	v_mfma_f32_32x32x16_bf16 v[82:97], v[162:165], v[242:245], v[82:97]
	v_mfma_f32_32x32x16_bf16 v[66:81], v[166:169], v[242:245], v[66:81]
	s_waitcnt lgkmcnt(0)
	v_mfma_f32_32x32x16_bf16 v[82:97], v[234:237], v[246:249], v[82:97]
	v_cvt_pk_bf16_f32 v234, v132, v133
	v_cvt_pk_bf16_f32 v236, v140, v141
	v_cvt_pk_bf16_f32 v235, v146, v147
	v_cvt_pk_bf16_f32 v237, v138, v139
	v_permlane32_swap_b32_e32 v234, v236
	s_nop 0
	v_permlane32_swap_b32_e32 v235, v237
	v_mfma_f32_32x32x16_bf16 v[66:81], v[238:241], v[246:249], v[66:81]
	ds_read_b64_tr_b16 v[238:239], v174 offset:0
	ds_read_b64_tr_b16 v[240:241], v174 offset:0x800
	ds_read_b64_tr_b16 v[242:243], v174 offset:0x1000
	ds_read_b64_tr_b16 v[244:245], v174 offset:0x1800
	ds_read_b64_tr_b16 v[246:247], v174 offset:0x2000
	ds_read_b64_tr_b16 v[248:249], v174 offset:0x2800
	ds_read_b64_tr_b16 v[204:205], v174 offset:0x3000
	ds_read_b64_tr_b16 v[206:207], v174 offset:0x3800
	s_nop 0
	s_waitcnt lgkmcnt(6)
	v_mfma_f32_32x32x16_bf16 v[2:17], v[152:155], v[238:241], v[2:17]
	s_waitcnt lgkmcnt(4)
	v_mfma_f32_32x32x16_bf16 v[2:17], v[156:159], v[242:245], v[2:17]
	s_waitcnt lgkmcnt(2)
	v_mfma_f32_32x32x16_bf16 v[2:17], v[230:233], v[246:249], v[2:17]
	s_waitcnt lgkmcnt(0)
	v_mfma_f32_32x32x16_bf16 v[2:17], v[234:237], v[204:207], v[2:17]
	ds_read_b64_tr_b16 v[204:205], v174 offset:0x200
	ds_read_b64_tr_b16 v[206:207], v174 offset:0xa00
	ds_read_b64_tr_b16 v[238:239], v174 offset:0x1200
	ds_read_b64_tr_b16 v[240:241], v174 offset:0x1a00
	ds_read_b64_tr_b16 v[242:243], v174 offset:0x2200
	ds_read_b64_tr_b16 v[244:245], v174 offset:0x2a00
	ds_read_b64_tr_b16 v[246:247], v174 offset:0x3200
	ds_read_b64_tr_b16 v[248:249], v174 offset:0x3a00
	s_nop 0
	s_waitcnt lgkmcnt(6)
	v_mfma_f32_32x32x16_bf16 v[50:65], v[152:155], v[204:207], v[50:65]
	ds_read_b64_tr_b16 v[204:205], v174 offset:0x400
	ds_read_b64_tr_b16 v[206:207], v174 offset:0xc00
	s_waitcnt lgkmcnt(6)
	v_mfma_f32_32x32x16_bf16 v[50:65], v[156:159], v[238:241], v[50:65]
	ds_read_b64_tr_b16 v[238:239], v174 offset:0x1400
	ds_read_b64_tr_b16 v[240:241], v174 offset:0x1c00
	s_waitcnt lgkmcnt(6)
	v_mfma_f32_32x32x16_bf16 v[50:65], v[230:233], v[242:245], v[50:65]
	ds_read_b64_tr_b16 v[242:243], v174 offset:0x2400
	ds_read_b64_tr_b16 v[244:245], v174 offset:0x2c00
	s_waitcnt lgkmcnt(6)
	v_mfma_f32_32x32x16_bf16 v[50:65], v[234:237], v[246:249], v[50:65]
	ds_read_b64_tr_b16 v[246:247], v174 offset:0x3400
	ds_read_b64_tr_b16 v[248:249], v174 offset:0x3c00
	s_waitcnt lgkmcnt(6)
	v_mfma_f32_32x32x16_bf16 v[34:49], v[152:155], v[204:207], v[34:49]
	ds_read_b64_tr_b16 v[204:205], v174 offset:0x600
	ds_read_b64_tr_b16 v[206:207], v174 offset:0xe00
	s_waitcnt lgkmcnt(6)
	v_mfma_f32_32x32x16_bf16 v[34:49], v[156:159], v[238:241], v[34:49]
	ds_read_b64_tr_b16 v[238:239], v174 offset:0x1600
	ds_read_b64_tr_b16 v[240:241], v174 offset:0x1e00
	s_waitcnt lgkmcnt(6)
	v_mfma_f32_32x32x16_bf16 v[34:49], v[230:233], v[242:245], v[34:49]
	ds_read_b64_tr_b16 v[242:243], v174 offset:0x2600
	ds_read_b64_tr_b16 v[244:245], v174 offset:0x2e00
	s_waitcnt lgkmcnt(6)
	v_mfma_f32_32x32x16_bf16 v[34:49], v[234:237], v[246:249], v[34:49]
	ds_read_b64_tr_b16 v[246:247], v174 offset:0x3600
	ds_read_b64_tr_b16 v[248:249], v174 offset:0x3e00
	s_waitcnt lgkmcnt(6)
	v_mfma_f32_32x32x16_bf16 v[18:33], v[152:155], v[204:207], v[18:33]
	v_max_f32_e32 v152, v83, v83
	v_max_f32_e32 v153, v82, v82
	v_max_f32_e32 v152, v153, v152
	v_max3_f32 v152, v152, v84, v85
	v_max3_f32 v152, v152, v86, v87
	v_max3_f32 v152, v152, v88, v89
	v_max3_f32 v152, v152, v90, v91
	v_max3_f32 v152, v152, v92, v93
	v_max3_f32 v152, v152, v94, v95
	s_waitcnt lgkmcnt(4)
	v_mfma_f32_32x32x16_bf16 v[18:33], v[156:159], v[238:241], v[18:33]
	v_max3_f32 v152, v152, v96, v97
	v_max3_f32 v152, v152, v66, v67
	v_max3_f32 v152, v152, v68, v69
	v_max3_f32 v152, v152, v70, v71
	v_max3_f32 v152, v152, v72, v73
	v_max3_f32 v152, v152, v74, v75
	v_max3_f32 v152, v152, v76, v77
	v_max3_f32 v152, v152, v78, v79
	s_waitcnt lgkmcnt(2)
	v_mfma_f32_32x32x16_bf16 v[18:33], v[230:233], v[242:245], v[18:33]
	v_max3_f32 v152, v152, v80, v81
	v_mov_b32_e32 v153, v152
	s_nop 1
	v_permlane32_swap_b32_e32 v152, v153
	v_max_f32_e32 v153, v153, v153
	v_max_f32_e32 v152, v152, v152
	v_max_f32_e32 v152, v152, v153
	v_sub_f32_e32 v153, v152, v214
	v_cmp_ge_f32_e32 vcc, s5, v153
	v_max_f32_e32 v153, v214, v214
	v_max_f32_e32 v152, v153, v152
	s_waitcnt lgkmcnt(0)
	v_mfma_f32_32x32x16_bf16 v[18:33], v[234:237], v[246:249], v[18:33]
	v_sub_f32_e32 v153, v214, v152
	v_mul_f32_e32 v153, 0x3dd53b94, v153
	v_exp_f32_e32 v153, v153
	s_cmp_eq_u64 vcc, exec
	s_cselect_b64 s[40:41], -1, 0
	s_cmp_lt_u32 s100, 0x2000
	s_cbranch_scc1 .Lmy_att_e1
	s_waitcnt vmcnt(0) lgkmcnt(0)
	s_barrier
.Lmy_att_e1:
	v_cndmask_b32_e64 v234, v153, 1.0, s[40:41]
	s_nop 0
	v_cmp_gt_f32_e32 vcc, 1.0, v234
	s_cbranch_vccz .LBB0_859
	s_and_saveexec_b64 s[0:1], s[38:39]
	ds_write_b32 v197, v234 offset:128
	s_or_b64 exec, exec, s[0:1]
	s_waitcnt lgkmcnt(0)
	ds_read_b128 v[132:135], v193 offset:224
	ds_read_b128 v[136:139], v193 offset:192
	ds_read_b128 v[140:143], v193 offset:160
	ds_read_b128 v[144:147], v193 offset:128
	s_waitcnt lgkmcnt(3)
	v_pk_mul_f32 v[16:17], v[16:17], v[134:135]
	s_waitcnt lgkmcnt(2)
	v_pk_mul_f32 v[12:13], v[12:13], v[138:139]
	s_waitcnt lgkmcnt(1)
	v_pk_mul_f32 v[8:9], v[8:9], v[142:143]
	s_waitcnt lgkmcnt(0)
	v_pk_mul_f32 v[4:5], v[4:5], v[146:147]
	v_pk_mul_f32 v[14:15], v[14:15], v[132:133]
	v_pk_mul_f32 v[10:11], v[10:11], v[136:137]
	v_pk_mul_f32 v[6:7], v[6:7], v[140:141]
	v_pk_mul_f32 v[2:3], v[2:3], v[144:145]
	v_pk_mul_f32 v[64:65], v[64:65], v[134:135]
	v_pk_mul_f32 v[60:61], v[60:61], v[138:139]
	v_pk_mul_f32 v[56:57], v[56:57], v[142:143]
	v_pk_mul_f32 v[52:53], v[52:53], v[146:147]
	v_pk_mul_f32 v[62:63], v[62:63], v[132:133]
	v_pk_mul_f32 v[58:59], v[58:59], v[136:137]
	v_pk_mul_f32 v[54:55], v[54:55], v[140:141]
	v_pk_mul_f32 v[50:51], v[50:51], v[144:145]
	v_pk_mul_f32 v[48:49], v[48:49], v[134:135]
	v_pk_mul_f32 v[44:45], v[44:45], v[138:139]
	v_pk_mul_f32 v[40:41], v[40:41], v[142:143]
	v_pk_mul_f32 v[36:37], v[36:37], v[146:147]
	v_pk_mul_f32 v[46:47], v[46:47], v[132:133]
	v_pk_mul_f32 v[42:43], v[42:43], v[136:137]
	v_pk_mul_f32 v[38:39], v[38:39], v[140:141]
	v_pk_mul_f32 v[34:35], v[34:35], v[144:145]
	v_pk_mul_f32 v[32:33], v[32:33], v[134:135]
	v_pk_mul_f32 v[28:29], v[28:29], v[138:139]
	v_pk_mul_f32 v[24:25], v[24:25], v[142:143]
	v_pk_mul_f32 v[20:21], v[20:21], v[146:147]
	v_pk_mul_f32 v[30:31], v[30:31], v[132:133]
	v_pk_mul_f32 v[26:27], v[26:27], v[136:137]
	v_pk_mul_f32 v[22:23], v[22:23], v[140:141]
	v_pk_mul_f32 v[18:19], v[18:19], v[144:145]
.LBB0_859:
	v_cndmask_b32_e64 v214, v152, v214, s[40:41]
	v_mul_f32_e32 v148, 0xbdd53b94, v214
	v_fmamk_f32 v82, v82, 0x3dd53b94, v148
	v_fmamk_f32 v83, v83, 0x3dd53b94, v148
	v_fmamk_f32 v84, v84, 0x3dd53b94, v148
	v_fmamk_f32 v85, v85, 0x3dd53b94, v148
	v_fmamk_f32 v86, v86, 0x3dd53b94, v148
	v_fmamk_f32 v87, v87, 0x3dd53b94, v148
	v_fmamk_f32 v88, v88, 0x3dd53b94, v148
	v_fmamk_f32 v89, v89, 0x3dd53b94, v148
	v_fmamk_f32 v90, v90, 0x3dd53b94, v148
	v_fmamk_f32 v91, v91, 0x3dd53b94, v148
	v_fmamk_f32 v92, v92, 0x3dd53b94, v148
	v_fmamk_f32 v93, v93, 0x3dd53b94, v148
	v_fmamk_f32 v94, v94, 0x3dd53b94, v148
	v_fmamk_f32 v95, v95, 0x3dd53b94, v148
	v_fmamk_f32 v96, v96, 0x3dd53b94, v148
	v_fmamk_f32 v97, v97, 0x3dd53b94, v148
	v_fmamk_f32 v152, v73, 0x3dd53b94, v148
	v_fmamk_f32 v153, v74, 0x3dd53b94, v148
	v_fmamk_f32 v157, v66, 0x3dd53b94, v148
	v_fmamk_f32 v158, v67, 0x3dd53b94, v148
	v_fmamk_f32 v159, v68, 0x3dd53b94, v148
	v_fmamk_f32 v229, v69, 0x3dd53b94, v148
	v_fmamk_f32 v230, v70, 0x3dd53b94, v148
	v_fmamk_f32 v150, v71, 0x3dd53b94, v148
	v_fmamk_f32 v151, v72, 0x3dd53b94, v148
	v_fmamk_f32 v154, v75, 0x3dd53b94, v148
	v_fmamk_f32 v155, v76, 0x3dd53b94, v148
	v_fmamk_f32 v156, v77, 0x3dd53b94, v148
	v_fmamk_f32 v149, v78, 0x3dd53b94, v148
	v_exp_f32_e32 v141, v82
	v_exp_f32_e32 v143, v83
	v_exp_f32_e32 v144, v84
	v_exp_f32_e32 v145, v85
	v_exp_f32_e32 v146, v86
	v_exp_f32_e32 v147, v87
	v_exp_f32_e32 v140, v88
	v_exp_f32_e32 v142, v89
	v_exp_f32_e32 v135, v90
	v_exp_f32_e32 v137, v91
	v_exp_f32_e32 v138, v92
	v_exp_f32_e32 v139, v93
	v_exp_f32_e32 v132, v94
	v_exp_f32_e32 v133, v95
	v_exp_f32_e32 v134, v96
	v_exp_f32_e32 v136, v97
	v_fmamk_f32 v231, v79, 0x3dd53b94, v148
	v_fmamk_f32 v232, v80, 0x3dd53b94, v148
	v_fmac_f32_e32 v148, 0x3dd53b94, v81
	s_cmp_ge_u32 s100, 0x2000
	s_cbranch_scc1 .Lmy_att_l1
	s_waitcnt vmcnt(0) lgkmcnt(0)
	s_barrier
.Lmy_att_l1:
	s_add_i32 m0, s100, 0x0
	s_nop 0
	global_load_lds_dwordx4 v178, s[14:15]
	s_add_i32 m0, s100, 0x400
	s_nop 0
	global_load_lds_dwordx4 v179, s[14:15]
	s_add_i32 s0, s12, 64
	s_cmp_lt_u32 s11, 2
	s_cselect_b32 s0, s0, s13
	s_ashr_i32 s1, s0, 31
	s_lshl_b64 s[14:15], s[0:1], 10
	s_add_u32 s14, s9, s14
	s_addc_u32 s15, s10, s15
	s_mul_hi_i32 s1, s0, 0x600
	s_mulk_i32 s0, 0x600
	s_add_u32 s0, s2, s0
	s_addc_u32 s1, s8, s1
	s_add_i32 m0, s101, 0xe000
	s_nop 0
	global_load_lds_dwordx4 v180, s[0:1]
	s_add_i32 m0, s101, 0xe400
	s_nop 0
	global_load_lds_dwordx4 v181, s[0:1]
	s_add_i32 m0, s101, 0xe800
	s_nop 0
	global_load_lds_dwordx4 v182, s[0:1]
	ds_read_b128 v[66:69], v183 offset:32768
	ds_read_b128 v[70:73], v183 offset:45056
	ds_read_b128 v[204:207], v184 offset:32768
	ds_read_b128 v[236:239], v184 offset:45056
	v_exp_f32_e32 v209, v152
	v_add_f32_e32 v152, 0, v141
	s_waitcnt lgkmcnt(2)
	v_mfma_f32_32x32x16_bf16 v[82:97], v[66:69], v[128:131], 0
	v_add_f32_e32 v152, v143, v152
	v_add_f32_e32 v152, v144, v152
	v_add_f32_e32 v152, v145, v152
	v_add_f32_e32 v152, v146, v152
	v_add_f32_e32 v152, v147, v152
	v_add_f32_e32 v152, v140, v152
	v_add_f32_e32 v152, v142, v152
	v_mfma_f32_32x32x16_bf16 v[66:81], v[70:73], v[128:131], 0
	ds_read_b128 v[162:165], v185 offset:32768
	ds_read_b128 v[166:169], v185 offset:45056
	v_add_f32_e32 v152, v135, v152
	v_add_f32_e32 v152, v137, v152
	v_add_f32_e32 v152, v138, v152
	v_add_f32_e32 v152, v139, v152
	v_add_f32_e32 v152, v132, v152
	v_add_f32_e32 v152, v133, v152
	v_add_f32_e32 v152, v134, v152
	s_waitcnt lgkmcnt(2)
	v_mfma_f32_32x32x16_bf16 v[82:97], v[204:207], v[124:127], v[82:97]
	v_add_f32_e32 v152, v136, v152
	v_exp_f32_e32 v208, v230
	v_exp_f32_e32 v150, v150
	v_exp_f32_e32 v151, v151
	v_exp_f32_e32 v210, v153
	v_exp_f32_e32 v211, v154
	v_exp_f32_e32 v233, v156
	v_mfma_f32_32x32x16_bf16 v[66:81], v[236:239], v[124:127], v[66:81]
	ds_read_b128 v[204:207], v186 offset:32768
	ds_read_b128 v[236:239], v186 offset:45056
	v_exp_f32_e32 v149, v149
	v_exp_f32_e32 v148, v148
	v_cvt_pk_bf16_f32 v153, v144, v145
	v_cvt_pk_bf16_f32 v154, v146, v147
	v_cvt_pk_bf16_f32 v156, v135, v137
	v_cvt_pk_bf16_f32 v230, v210, v211
	s_waitcnt lgkmcnt(2)
	v_mfma_f32_32x32x16_bf16 v[82:97], v[162:165], v[120:123], v[82:97]
	v_mfma_f32_32x32x16_bf16 v[66:81], v[166:169], v[120:123], v[66:81]
	ds_read_b128 v[162:165], v187 offset:32768
	ds_read_b128 v[166:169], v187 offset:45056
	s_waitcnt lgkmcnt(2)
	v_mfma_f32_32x32x16_bf16 v[82:97], v[204:207], v[116:119], v[82:97]
	v_mfma_f32_32x32x16_bf16 v[66:81], v[236:239], v[116:119], v[66:81]
	ds_read_b128 v[204:207], v188 offset:32768
	ds_read_b128 v[236:239], v188 offset:45056
	s_waitcnt lgkmcnt(2)
	v_mfma_f32_32x32x16_bf16 v[82:97], v[162:165], v[112:115], v[82:97]
	v_mfma_f32_32x32x16_bf16 v[66:81], v[166:169], v[112:115], v[66:81]
	ds_read_b128 v[162:165], v189 offset:32768
	ds_read_b128 v[166:169], v189 offset:45056
	s_waitcnt lgkmcnt(2)
	v_mfma_f32_32x32x16_bf16 v[82:97], v[204:207], v[108:111], v[82:97]
	v_mfma_f32_32x32x16_bf16 v[66:81], v[236:239], v[108:111], v[66:81]
	ds_read_b128 v[204:207], v190 offset:32768
	ds_read_b128 v[236:239], v190 offset:45056
	s_waitcnt lgkmcnt(2)
	v_mfma_f32_32x32x16_bf16 v[82:97], v[162:165], v[104:107], v[82:97]
	v_mfma_f32_32x32x16_bf16 v[66:81], v[166:169], v[104:107], v[66:81]
	ds_read_b128 v[162:165], v191 offset:32768
	ds_read_b128 v[166:169], v191 offset:45056
	ds_read_b128 v[240:243], v192
	s_waitcnt lgkmcnt(3)
	v_mfma_f32_32x32x16_bf16 v[82:97], v[204:207], v[100:103], v[82:97]
	v_mfma_f32_32x32x16_bf16 v[66:81], v[236:239], v[100:103], v[66:81]
	ds_read_b128 v[204:207], v194 offset:32768
	ds_read_b128 v[236:239], v194 offset:45056
	ds_read_b128 v[244:247], v176
	s_waitcnt lgkmcnt(3)
	v_mfma_f32_32x32x16_bf16 v[82:97], v[162:165], v[240:243], v[82:97]
	v_mfma_f32_32x32x16_bf16 v[66:81], v[166:169], v[240:243], v[66:81]
	ds_read_b128 v[162:165], v195 offset:32768
	ds_read_b128 v[166:169], v195 offset:45056
	ds_read_b128 v[240:243], v177
	s_waitcnt lgkmcnt(3)
	v_mfma_f32_32x32x16_bf16 v[82:97], v[204:207], v[244:247], v[82:97]
	v_mfma_f32_32x32x16_bf16 v[66:81], v[236:239], v[244:247], v[66:81]
	ds_read_b128 v[204:207], v196 offset:32768
	ds_read_b128 v[236:239], v196 offset:45056
	ds_read_b128 v[244:247], v175
	s_waitcnt lgkmcnt(3)
	v_mfma_f32_32x32x16_bf16 v[82:97], v[162:165], v[240:243], v[82:97]
	v_mfma_f32_32x32x16_bf16 v[66:81], v[166:169], v[240:243], v[66:81]
	s_waitcnt lgkmcnt(0)
	v_mfma_f32_32x32x16_bf16 v[82:97], v[204:207], v[244:247], v[82:97]
	v_exp_f32_e32 v204, v157
	v_exp_f32_e32 v205, v158
	v_exp_f32_e32 v206, v159
	v_exp_f32_e32 v207, v229
	v_add_f32_e32 v152, v204, v152
	v_add_f32_e32 v152, v205, v152
	v_add_f32_e32 v152, v206, v152
	v_add_f32_e32 v152, v207, v152
	v_add_f32_e32 v152, v208, v152
	v_add_f32_e32 v152, v150, v152
	v_exp_f32_e32 v229, v155
	v_add_f32_e32 v152, v151, v152
	v_add_f32_e32 v152, v209, v152
	v_add_f32_e32 v152, v210, v152
	v_mfma_f32_32x32x16_bf16 v[66:81], v[236:239], v[244:247], v[66:81]
	v_exp_f32_e32 v237, v231
	v_add_f32_e32 v152, v211, v152
	v_exp_f32_e32 v238, v232
	v_add_f32_e32 v152, v229, v152
	v_add_f32_e32 v152, v233, v152
	v_add_f32_e32 v152, v149, v152
	v_add_f32_e32 v152, v237, v152
	v_add_f32_e32 v152, v238, v152
	v_add_f32_e32 v235, v148, v152
	v_mov_b32_e32 v236, v235
	v_cvt_pk_bf16_f32 v152, v141, v143
	v_cvt_pk_bf16_f32 v155, v140, v142
	v_permlane32_swap_b32_e32 v235, v236
	v_permlane32_swap_b32_e32 v152, v154
	v_permlane32_swap_b32_e32 v153, v155
	v_cvt_pk_bf16_f32 v157, v138, v139
	v_cvt_pk_bf16_f32 v158, v132, v133
	v_cvt_pk_bf16_f32 v159, v134, v136
	v_cvt_pk_bf16_f32 v204, v204, v205
	v_cvt_pk_bf16_f32 v205, v206, v207
	v_cvt_pk_bf16_f32 v206, v208, v150
	v_cvt_pk_bf16_f32 v207, v151, v209
	v_cvt_pk_bf16_f32 v231, v229, v233
	v_cvt_pk_bf16_f32 v232, v149, v237
	v_cvt_pk_bf16_f32 v233, v238, v148
	v_permlane32_swap_b32_e32 v156, v158
	v_permlane32_swap_b32_e32 v157, v159
	v_permlane32_swap_b32_e32 v204, v206
	v_permlane32_swap_b32_e32 v205, v207
	v_permlane32_swap_b32_e32 v230, v232
	v_permlane32_swap_b32_e32 v231, v233
	ds_read_b64_tr_b16 v[238:239], v199 offset:0
	ds_read_b64_tr_b16 v[240:241], v199 offset:0x800
	ds_read_b64_tr_b16 v[242:243], v199 offset:0x1000
	ds_read_b64_tr_b16 v[244:245], v199 offset:0x1800
	ds_read_b64_tr_b16 v[246:247], v199 offset:0x2000
	ds_read_b64_tr_b16 v[248:249], v199 offset:0x2800
	ds_read_b64_tr_b16 v[208:209], v199 offset:0x3000
	ds_read_b64_tr_b16 v[210:211], v199 offset:0x3800
	s_nop 0
	s_waitcnt lgkmcnt(6)
	v_mfma_f32_32x32x16_bf16 v[2:17], v[152:155], v[238:241], v[2:17]
	s_waitcnt lgkmcnt(4)
	v_mfma_f32_32x32x16_bf16 v[2:17], v[156:159], v[242:245], v[2:17]
	s_waitcnt lgkmcnt(2)
	v_mfma_f32_32x32x16_bf16 v[2:17], v[204:207], v[246:249], v[2:17]
	s_waitcnt lgkmcnt(0)
	v_mfma_f32_32x32x16_bf16 v[2:17], v[230:233], v[208:211], v[2:17]
	ds_read_b64_tr_b16 v[208:209], v199 offset:0x200
	ds_read_b64_tr_b16 v[210:211], v199 offset:0xa00
	ds_read_b64_tr_b16 v[238:239], v199 offset:0x1200
	ds_read_b64_tr_b16 v[240:241], v199 offset:0x1a00
	ds_read_b64_tr_b16 v[242:243], v199 offset:0x2200
	ds_read_b64_tr_b16 v[244:245], v199 offset:0x2a00
	ds_read_b64_tr_b16 v[246:247], v199 offset:0x3200
	ds_read_b64_tr_b16 v[248:249], v199 offset:0x3a00
	s_nop 0
	s_waitcnt lgkmcnt(6)
	v_mfma_f32_32x32x16_bf16 v[50:65], v[152:155], v[208:211], v[50:65]
	ds_read_b64_tr_b16 v[208:209], v199 offset:0x400
	ds_read_b64_tr_b16 v[210:211], v199 offset:0xc00
	s_waitcnt lgkmcnt(6)
	v_mfma_f32_32x32x16_bf16 v[50:65], v[156:159], v[238:241], v[50:65]
	ds_read_b64_tr_b16 v[238:239], v199 offset:0x1400
	ds_read_b64_tr_b16 v[240:241], v199 offset:0x1c00
	s_waitcnt lgkmcnt(6)
	v_mfma_f32_32x32x16_bf16 v[50:65], v[204:207], v[242:245], v[50:65]
	ds_read_b64_tr_b16 v[242:243], v199 offset:0x2400
	ds_read_b64_tr_b16 v[244:245], v199 offset:0x2c00
	s_waitcnt lgkmcnt(6)
	v_mfma_f32_32x32x16_bf16 v[50:65], v[230:233], v[246:249], v[50:65]
	ds_read_b64_tr_b16 v[246:247], v199 offset:0x3400
	ds_read_b64_tr_b16 v[248:249], v199 offset:0x3c00
	s_waitcnt lgkmcnt(6)
	v_mfma_f32_32x32x16_bf16 v[34:49], v[152:155], v[208:211], v[34:49]
	ds_read_b64_tr_b16 v[208:209], v199 offset:0x600
	ds_read_b64_tr_b16 v[210:211], v199 offset:0xe00
	s_waitcnt lgkmcnt(6)
	v_mfma_f32_32x32x16_bf16 v[34:49], v[156:159], v[238:241], v[34:49]
	ds_read_b64_tr_b16 v[238:239], v199 offset:0x1600
	ds_read_b64_tr_b16 v[240:241], v199 offset:0x1e00
	s_waitcnt lgkmcnt(6)
	v_mfma_f32_32x32x16_bf16 v[34:49], v[204:207], v[242:245], v[34:49]
	ds_read_b64_tr_b16 v[242:243], v199 offset:0x2600
	ds_read_b64_tr_b16 v[244:245], v199 offset:0x2e00
	s_waitcnt lgkmcnt(6)
	v_mfma_f32_32x32x16_bf16 v[34:49], v[230:233], v[246:249], v[34:49]
	ds_read_b64_tr_b16 v[246:247], v199 offset:0x3600
	ds_read_b64_tr_b16 v[248:249], v199 offset:0x3e00
	s_waitcnt lgkmcnt(6)
	v_mfma_f32_32x32x16_bf16 v[18:33], v[152:155], v[208:211], v[18:33]
	v_max_f32_e32 v152, v83, v83
	v_max_f32_e32 v153, v82, v82
	v_max_f32_e32 v152, v153, v152
	v_max3_f32 v152, v152, v84, v85
	v_max3_f32 v152, v152, v86, v87
	v_max3_f32 v152, v152, v88, v89
	v_max3_f32 v152, v152, v90, v91
	v_max3_f32 v152, v152, v92, v93
	v_max3_f32 v152, v152, v94, v95
	s_waitcnt lgkmcnt(4)
	v_mfma_f32_32x32x16_bf16 v[18:33], v[156:159], v[238:241], v[18:33]
	v_max3_f32 v152, v152, v96, v97
	v_max3_f32 v152, v152, v66, v67
	v_max3_f32 v152, v152, v68, v69
	v_max3_f32 v152, v152, v70, v71
	v_max3_f32 v152, v152, v72, v73
	v_max3_f32 v152, v152, v74, v75
	v_max3_f32 v152, v152, v76, v77
	v_max3_f32 v152, v152, v78, v79
	s_waitcnt lgkmcnt(2)
	v_mfma_f32_32x32x16_bf16 v[18:33], v[204:207], v[242:245], v[18:33]
	v_max3_f32 v152, v152, v80, v81
	v_mov_b32_e32 v153, v152
	s_nop 1
	v_permlane32_swap_b32_e32 v152, v153
	v_max_f32_e32 v153, v153, v153
	v_max_f32_e32 v152, v152, v152
	v_max_f32_e32 v152, v152, v153
	v_sub_f32_e32 v153, v152, v214
	v_cmp_ge_f32_e32 vcc, s5, v153
	v_max_f32_e32 v153, v214, v214
	v_max_f32_e32 v153, v153, v152
	s_waitcnt lgkmcnt(0)
	v_mfma_f32_32x32x16_bf16 v[18:33], v[230:233], v[246:249], v[18:33]
	v_sub_f32_e32 v152, v214, v153
	v_mul_f32_e32 v152, 0x3dd53b94, v152
	v_exp_f32_e32 v152, v152
	s_cmp_eq_u64 vcc, exec
	s_cselect_b64 s[40:41], -1, 0
	s_cmp_lt_u32 s100, 0x2000
	s_cbranch_scc1 .Lmy_att_e2
	s_waitcnt vmcnt(0) lgkmcnt(0)
	s_barrier
.Lmy_att_e2:
	v_cndmask_b32_e64 v152, v152, 1.0, s[40:41]
	s_nop 0
	v_cmp_gt_f32_e32 vcc, 1.0, v152
	s_cbranch_vccz .LBB0_863
	s_and_saveexec_b64 s[0:1], s[38:39]
	ds_write_b32 v197, v152 offset:128
	s_or_b64 exec, exec, s[0:1]
	s_waitcnt lgkmcnt(0)
	ds_read_b128 v[132:135], v193 offset:224
	ds_read_b128 v[136:139], v193 offset:192
	ds_read_b128 v[140:143], v193 offset:160
	ds_read_b128 v[144:147], v193 offset:128
	s_waitcnt lgkmcnt(3)
	v_pk_mul_f32 v[16:17], v[16:17], v[134:135]
	s_waitcnt lgkmcnt(2)
	v_pk_mul_f32 v[12:13], v[12:13], v[138:139]
	s_waitcnt lgkmcnt(1)
	v_pk_mul_f32 v[8:9], v[8:9], v[142:143]
	s_waitcnt lgkmcnt(0)
	v_pk_mul_f32 v[4:5], v[4:5], v[146:147]
	v_pk_mul_f32 v[14:15], v[14:15], v[132:133]
	v_pk_mul_f32 v[10:11], v[10:11], v[136:137]
	v_pk_mul_f32 v[6:7], v[6:7], v[140:141]
	v_pk_mul_f32 v[2:3], v[2:3], v[144:145]
	v_pk_mul_f32 v[64:65], v[64:65], v[134:135]
	v_pk_mul_f32 v[60:61], v[60:61], v[138:139]
	v_pk_mul_f32 v[56:57], v[56:57], v[142:143]
	v_pk_mul_f32 v[52:53], v[52:53], v[146:147]
	v_pk_mul_f32 v[62:63], v[62:63], v[132:133]
	v_pk_mul_f32 v[58:59], v[58:59], v[136:137]
	v_pk_mul_f32 v[54:55], v[54:55], v[140:141]
	v_pk_mul_f32 v[50:51], v[50:51], v[144:145]
	v_pk_mul_f32 v[48:49], v[48:49], v[134:135]
	v_pk_mul_f32 v[44:45], v[44:45], v[138:139]
	v_pk_mul_f32 v[40:41], v[40:41], v[142:143]
	v_pk_mul_f32 v[36:37], v[36:37], v[146:147]
	v_pk_mul_f32 v[46:47], v[46:47], v[132:133]
	v_pk_mul_f32 v[42:43], v[42:43], v[136:137]
	v_pk_mul_f32 v[38:39], v[38:39], v[140:141]
	v_pk_mul_f32 v[34:35], v[34:35], v[144:145]
	v_pk_mul_f32 v[32:33], v[32:33], v[134:135]
	v_pk_mul_f32 v[28:29], v[28:29], v[138:139]
	v_pk_mul_f32 v[24:25], v[24:25], v[142:143]
	v_pk_mul_f32 v[20:21], v[20:21], v[146:147]
	v_pk_mul_f32 v[30:31], v[30:31], v[132:133]
	v_pk_mul_f32 v[26:27], v[26:27], v[136:137]
	v_pk_mul_f32 v[22:23], v[22:23], v[140:141]
	v_pk_mul_f32 v[18:19], v[18:19], v[144:145]
.LBB0_863:
	v_cndmask_b32_e64 v214, v153, v214, s[40:41]
	v_mul_f32_e32 v138, 0xbdd53b94, v214
	v_mov_b32_e32 v139, v138
	v_fmamk_f32 v82, v82, 0x3dd53b94, v138
	v_fmamk_f32 v83, v83, 0x3dd53b94, v138
	v_fmamk_f32 v84, v84, 0x3dd53b94, v138
	v_fmamk_f32 v85, v85, 0x3dd53b94, v138
	v_fmamk_f32 v86, v86, 0x3dd53b94, v138
	v_fmamk_f32 v87, v87, 0x3dd53b94, v138
	v_fmamk_f32 v88, v88, 0x3dd53b94, v138
	v_fmamk_f32 v89, v89, 0x3dd53b94, v138
	v_fmamk_f32 v90, v90, 0x3dd53b94, v138
	v_fmamk_f32 v91, v91, 0x3dd53b94, v138
	v_fmamk_f32 v92, v92, 0x3dd53b94, v138
	v_fmamk_f32 v93, v93, 0x3dd53b94, v138
	v_fmamk_f32 v94, v94, 0x3dd53b94, v138
	v_fmamk_f32 v95, v95, 0x3dd53b94, v138
	v_fmamk_f32 v96, v96, 0x3dd53b94, v138
	v_fmac_f32_e32 v139, 0x3dd53b94, v97
	v_exp_f32_e32 v153, v82
	v_exp_f32_e32 v154, v83
	v_exp_f32_e32 v230, v84
	v_exp_f32_e32 v231, v85
	v_exp_f32_e32 v232, v86
	v_exp_f32_e32 v233, v87
	v_exp_f32_e32 v155, v88
	v_exp_f32_e32 v229, v89
	v_exp_f32_e32 v151, v90
	v_exp_f32_e32 v156, v91
	v_exp_f32_e32 v157, v92
	v_exp_f32_e32 v158, v93
	v_exp_f32_e32 v148, v94
	v_exp_f32_e32 v149, v95
	v_exp_f32_e32 v150, v96
	v_exp_f32_e32 v159, v139
	v_pk_fma_f32 v[144:145], v[66:67], s[30:31], v[138:139] op_sel_hi:[1,0,0]
	v_add_f32_e32 v66, v227, v228
	v_fmac_f32_e32 v66, v213, v198
	v_add_f32_e32 v198, v235, v236
	s_addk_i32 s12, 0x80
	s_addk_i32 s13, 0x80
	v_pk_fma_f32 v[142:143], v[68:69], s[30:31], v[138:139] op_sel_hi:[1,0,0]
	v_pk_fma_f32 v[136:137], v[70:71], s[30:31], v[138:139] op_sel_hi:[1,0,0]
	v_pk_fma_f32 v[134:135], v[72:73], s[30:31], v[138:139] op_sel_hi:[1,0,0]
	v_pk_fma_f32 v[132:133], v[74:75], s[30:31], v[138:139] op_sel_hi:[1,0,0]
	v_pk_fma_f32 v[146:147], v[76:77], s[30:31], v[138:139] op_sel_hi:[1,0,0]
	v_pk_fma_f32 v[140:141], v[78:79], s[30:31], v[138:139] op_sel_hi:[1,0,0]
	v_pk_fma_f32 v[138:139], v[80:81], s[30:31], v[138:139] op_sel_hi:[1,0,0]
	v_fmac_f32_e32 v198, v66, v234
	s_cmp_ge_u32 s100, 0x2000
	s_cbranch_scc1 .Lmy_att_l2
	s_waitcnt vmcnt(0) lgkmcnt(0)
	s_barrier
.Lmy_att_l2:
	s_cmp_gt_u32 s11, 32
	s_cbranch_scc1 .LBB0_865
	v_mov_b32_e32 v213, v152
	s_branch .LBB0_855
